# MT3 residual epilogues (OUT/XO/DOWN) via no-return global_atomic_add_f32 (same single f32 add, one lane per address) instead of load+add+store
# baseline (speedup 1.0000x reference)
; DI int otid() { int t = threadIdx.x; asm volatile("" : "+v"(t)); return t; }
; DI int crow(int i, int h) { return (i & 3) + 8 * (i >> 2) + 4 * h; }
; DI const bf16_t* wp(const Params& p, int l, size_t off) { return (const bf16_t*)(p.ws + OFF_WP) + (size_t)l * PW_LAYER + off; }
;     DI void operator()(int unit, const f32x16 (&acc)[MT][NT]) const {
;         const int lane = otid() & 63, r = lane & 31, h = lane >> 5;
; #pragma unroll
;         for (int mi = 0; mi < MT; ++mi)
; #pragma unroll
;             for (int nj = 0; nj < NT; ++nj)
; #pragma unroll
;                 for (int i = 0; i < 16; ++i) { float* q = x + ((mi * 32 + crow(i, h) + (mi == 2 ? d2 : 0)) * DM + unit * UW + nj * 32 + r); *q = *q + acc[mi][nj][i]; if (i == 15) __builtin_amdgcn_sched_barrier(0); }
; template <int MT> DI void phaseB(const Params& p, int l, int t, unsigned char* lds) {
;     ...
;     gemm64<1024, MT>(priv + PC_M, PRIVW, d2, wp(p, l, PW_OUT), DM / UW, lds, EpiResid<MT>{x, d2});
.LBB0_416:
	s_and_saveexec_b64 s[56:57], s[4:5]
	s_cbranch_execz .LBB0_405
	s_waitcnt vmcnt(0)
	v_and_b32_e32 v2, 31, v176
	v_lshlrev_b32_e32 v3, 9, v176
	v_and_b32_e32 v3, 0x4000, v3
	v_lshl_or_b32 v4, v2, 2, v3
	v_lshl_add_u32 v4, v232, 8, v4
	v_add_u32_e32 v5, 0x1000, v4
	global_atomic_add_f32 v5, v96, s[0:1] offset:-4096
	global_atomic_add_f32 v5, v80, s[0:1] offset:-3968
	global_atomic_add_f32 v5, v97, s[0:1] offset:0
	global_atomic_add_f32 v5, v81, s[0:1] offset:128
	v_add_u32_e32 v6, 0x3000, v4
	global_atomic_add_f32 v6, v98, s[0:1] offset:-4096
	global_atomic_add_f32 v6, v82, s[0:1] offset:-3968
	global_atomic_add_f32 v6, v99, s[0:1] offset:0
	global_atomic_add_f32 v6, v83, s[0:1] offset:128
	v_add_u32_e32 v7, 0x9000, v4
	global_atomic_add_f32 v7, v100, s[0:1] offset:-4096
	global_atomic_add_f32 v7, v84, s[0:1] offset:-3968
	global_atomic_add_f32 v7, v101, s[0:1] offset:0
	global_atomic_add_f32 v7, v85, s[0:1] offset:128
	v_add_u32_e32 v8, 0xb000, v4
	global_atomic_add_f32 v8, v102, s[0:1] offset:-4096
	global_atomic_add_f32 v8, v86, s[0:1] offset:-3968
	global_atomic_add_f32 v8, v103, s[0:1] offset:0
	global_atomic_add_f32 v8, v87, s[0:1] offset:128
	v_add_u32_e32 v9, 0x11000, v4
	global_atomic_add_f32 v9, v104, s[0:1] offset:-4096
	global_atomic_add_f32 v9, v88, s[0:1] offset:-3968
	global_atomic_add_f32 v9, v105, s[0:1] offset:0
	global_atomic_add_f32 v9, v89, s[0:1] offset:128
	v_add_u32_e32 v10, 0x13000, v4
	global_atomic_add_f32 v10, v106, s[0:1] offset:-4096
	global_atomic_add_f32 v10, v90, s[0:1] offset:-3968
	global_atomic_add_f32 v10, v107, s[0:1] offset:0
	global_atomic_add_f32 v10, v91, s[0:1] offset:128
	v_add_u32_e32 v11, 0x19000, v4
	global_atomic_add_f32 v11, v108, s[0:1] offset:-4096
	global_atomic_add_f32 v11, v92, s[0:1] offset:-3968
	global_atomic_add_f32 v11, v109, s[0:1] offset:0
	global_atomic_add_f32 v11, v93, s[0:1] offset:128
	v_add_u32_e32 v12, 0x1b000, v4
	global_atomic_add_f32 v12, v110, s[0:1] offset:-4096
	global_atomic_add_f32 v12, v94, s[0:1] offset:-3968
	global_atomic_add_f32 v12, v111, s[0:1] offset:0
	global_atomic_add_f32 v12, v95, s[0:1] offset:128
	v_add_u32_e32 v5, 0x21000, v4
	global_atomic_add_f32 v5, v64, s[0:1] offset:-4096
	global_atomic_add_f32 v5, v48, s[0:1] offset:-3968
	global_atomic_add_f32 v5, v65, s[0:1] offset:0
	global_atomic_add_f32 v5, v49, s[0:1] offset:128
	v_add_u32_e32 v6, 0x23000, v4
	global_atomic_add_f32 v6, v66, s[0:1] offset:-4096
	global_atomic_add_f32 v6, v50, s[0:1] offset:-3968
	global_atomic_add_f32 v6, v67, s[0:1] offset:0
	global_atomic_add_f32 v6, v51, s[0:1] offset:128
	v_add_u32_e32 v7, 0x29000, v4
	global_atomic_add_f32 v7, v68, s[0:1] offset:-4096
	global_atomic_add_f32 v7, v52, s[0:1] offset:-3968
	global_atomic_add_f32 v7, v69, s[0:1] offset:0
	global_atomic_add_f32 v7, v53, s[0:1] offset:128
	v_add_u32_e32 v8, 0x2b000, v4
	global_atomic_add_f32 v8, v70, s[0:1] offset:-4096
	global_atomic_add_f32 v8, v54, s[0:1] offset:-3968
	global_atomic_add_f32 v8, v71, s[0:1] offset:0
	global_atomic_add_f32 v8, v55, s[0:1] offset:128
	v_add_u32_e32 v9, 0x31000, v4
	global_atomic_add_f32 v9, v72, s[0:1] offset:-4096
	global_atomic_add_f32 v9, v56, s[0:1] offset:-3968
	global_atomic_add_f32 v9, v73, s[0:1] offset:0
	global_atomic_add_f32 v9, v57, s[0:1] offset:128
	v_add_u32_e32 v10, 0x33000, v4
	global_atomic_add_f32 v10, v74, s[0:1] offset:-4096
	global_atomic_add_f32 v10, v58, s[0:1] offset:-3968
	global_atomic_add_f32 v10, v75, s[0:1] offset:0
	global_atomic_add_f32 v10, v59, s[0:1] offset:128
	v_add_u32_e32 v11, 0x39000, v4
	global_atomic_add_f32 v11, v76, s[0:1] offset:-4096
	global_atomic_add_f32 v11, v60, s[0:1] offset:-3968
	global_atomic_add_f32 v11, v77, s[0:1] offset:0
	global_atomic_add_f32 v11, v61, s[0:1] offset:128
	v_add_u32_e32 v12, 0x3b000, v4
	global_atomic_add_f32 v12, v78, s[0:1] offset:-4096
	global_atomic_add_f32 v12, v62, s[0:1] offset:-3968
	global_atomic_add_f32 v12, v79, s[0:1] offset:0
	global_atomic_add_f32 v12, v63, s[0:1] offset:128
	v_lshl_add_u32 v3, s59, 12, v4
	v_add_u32_e32 v5, 0x1000, v3
	global_atomic_add_f32 v5, v32, s[0:1] offset:-4096
	global_atomic_add_f32 v5, v16, s[0:1] offset:-3968
	global_atomic_add_f32 v5, v33, s[0:1] offset:0
	global_atomic_add_f32 v5, v17, s[0:1] offset:128
	v_add_u32_e32 v6, 0x3000, v3
	global_atomic_add_f32 v6, v34, s[0:1] offset:-4096
	global_atomic_add_f32 v6, v18, s[0:1] offset:-3968
	global_atomic_add_f32 v6, v35, s[0:1] offset:0
	global_atomic_add_f32 v6, v19, s[0:1] offset:128
	v_add_u32_e32 v7, 0x9000, v3
	global_atomic_add_f32 v7, v36, s[0:1] offset:-4096
	global_atomic_add_f32 v7, v20, s[0:1] offset:-3968
	global_atomic_add_f32 v7, v37, s[0:1] offset:0
	global_atomic_add_f32 v7, v21, s[0:1] offset:128
	v_add_u32_e32 v8, 0xb000, v3
	global_atomic_add_f32 v8, v38, s[0:1] offset:-4096
	global_atomic_add_f32 v8, v22, s[0:1] offset:-3968
	global_atomic_add_f32 v8, v39, s[0:1] offset:0
	global_atomic_add_f32 v8, v23, s[0:1] offset:128
	v_add_u32_e32 v9, 0x11000, v3
	global_atomic_add_f32 v9, v40, s[0:1] offset:-4096
	global_atomic_add_f32 v9, v24, s[0:1] offset:-3968
	global_atomic_add_f32 v9, v41, s[0:1] offset:0
	global_atomic_add_f32 v9, v25, s[0:1] offset:128
	v_add_u32_e32 v10, 0x13000, v3
	global_atomic_add_f32 v10, v42, s[0:1] offset:-4096
	global_atomic_add_f32 v10, v26, s[0:1] offset:-3968
	global_atomic_add_f32 v10, v43, s[0:1] offset:0
	global_atomic_add_f32 v10, v27, s[0:1] offset:128
	v_add_u32_e32 v11, 0x19000, v3
	global_atomic_add_f32 v11, v44, s[0:1] offset:-4096
	global_atomic_add_f32 v11, v28, s[0:1] offset:-3968
	global_atomic_add_f32 v11, v45, s[0:1] offset:0
	global_atomic_add_f32 v11, v29, s[0:1] offset:128
	v_add_u32_e32 v12, 0x1b000, v3
	global_atomic_add_f32 v12, v46, s[0:1] offset:-4096
	global_atomic_add_f32 v12, v30, s[0:1] offset:-3968
	global_atomic_add_f32 v12, v47, s[0:1] offset:0
	global_atomic_add_f32 v12, v31, s[0:1] offset:128
	s_waitcnt vmcnt(0)
	s_branch .LBB0_405

; DI int otid() { int t = threadIdx.x; asm volatile("" : "+v"(t)); return t; }
; DI int crow(int i, int h) { return (i & 3) + 8 * (i >> 2) + 4 * h; }
; DI const bf16_t* wp(const Params& p, int l, size_t off) { return (const bf16_t*)(p.ws + OFF_WP) + (size_t)l * PW_LAYER + off; }
;     DI void operator()(int unit, const f32x16 (&acc)[MT][NT]) const {
;         const int lane = otid() & 63, r = lane & 31, h = lane >> 5;
; #pragma unroll
;         for (int mi = 0; mi < MT; ++mi)
; #pragma unroll
;             for (int nj = 0; nj < NT; ++nj)
; #pragma unroll
;                 for (int i = 0; i < 16; ++i) { float* q = x + ((mi * 32 + crow(i, h) + (mi == 2 ? d2 : 0)) * DM + unit * UW + nj * 32 + r); *q = *q + acc[mi][nj][i]; if (i == 15) __builtin_amdgcn_sched_barrier(0); }
; template <int MT> DI void phaseB(const Params& p, int l, int t, unsigned char* lds) {
;     ...
;     gemm64<512, MT>(priv + PC_OX, PRIVW, d2, wp(p, l, PW_XO), DM / UW, lds, EpiResid<MT>{x, d2});
.LBB0_455:
	s_and_saveexec_b64 s[28:29], s[4:5]
	s_cbranch_execz .LBB0_444
	s_waitcnt vmcnt(0)
	v_and_b32_e32 v2, 31, v176
	v_lshlrev_b32_e32 v3, 9, v176
	v_and_b32_e32 v3, 0x4000, v3
	v_lshl_or_b32 v4, v2, 2, v3
	v_lshl_add_u32 v4, v238, 8, v4
	v_add_u32_e32 v5, 0x1000, v4
	global_atomic_add_f32 v5, v96, s[0:1] offset:-4096
	global_atomic_add_f32 v5, v80, s[0:1] offset:-3968
	global_atomic_add_f32 v5, v97, s[0:1] offset:0
	global_atomic_add_f32 v5, v81, s[0:1] offset:128
	v_add_u32_e32 v6, 0x3000, v4
	global_atomic_add_f32 v6, v98, s[0:1] offset:-4096
	global_atomic_add_f32 v6, v82, s[0:1] offset:-3968
	global_atomic_add_f32 v6, v99, s[0:1] offset:0
	global_atomic_add_f32 v6, v83, s[0:1] offset:128
	v_add_u32_e32 v7, 0x9000, v4
	global_atomic_add_f32 v7, v100, s[0:1] offset:-4096
	global_atomic_add_f32 v7, v84, s[0:1] offset:-3968
	global_atomic_add_f32 v7, v101, s[0:1] offset:0
	global_atomic_add_f32 v7, v85, s[0:1] offset:128
	v_add_u32_e32 v8, 0xb000, v4
	global_atomic_add_f32 v8, v102, s[0:1] offset:-4096
	global_atomic_add_f32 v8, v86, s[0:1] offset:-3968
	global_atomic_add_f32 v8, v103, s[0:1] offset:0
	global_atomic_add_f32 v8, v87, s[0:1] offset:128
	v_add_u32_e32 v9, 0x11000, v4
	global_atomic_add_f32 v9, v104, s[0:1] offset:-4096
	global_atomic_add_f32 v9, v88, s[0:1] offset:-3968
	global_atomic_add_f32 v9, v105, s[0:1] offset:0
	global_atomic_add_f32 v9, v89, s[0:1] offset:128
	v_add_u32_e32 v10, 0x13000, v4
	global_atomic_add_f32 v10, v106, s[0:1] offset:-4096
	global_atomic_add_f32 v10, v90, s[0:1] offset:-3968
	global_atomic_add_f32 v10, v107, s[0:1] offset:0
	global_atomic_add_f32 v10, v91, s[0:1] offset:128
	v_add_u32_e32 v11, 0x19000, v4
	global_atomic_add_f32 v11, v108, s[0:1] offset:-4096
	global_atomic_add_f32 v11, v92, s[0:1] offset:-3968
	global_atomic_add_f32 v11, v109, s[0:1] offset:0
	global_atomic_add_f32 v11, v93, s[0:1] offset:128
	v_add_u32_e32 v12, 0x1b000, v4
	global_atomic_add_f32 v12, v110, s[0:1] offset:-4096
	global_atomic_add_f32 v12, v94, s[0:1] offset:-3968
	global_atomic_add_f32 v12, v111, s[0:1] offset:0
	global_atomic_add_f32 v12, v95, s[0:1] offset:128
	v_add_u32_e32 v5, 0x21000, v4
	global_atomic_add_f32 v5, v64, s[0:1] offset:-4096
	global_atomic_add_f32 v5, v48, s[0:1] offset:-3968
	global_atomic_add_f32 v5, v65, s[0:1] offset:0
	global_atomic_add_f32 v5, v49, s[0:1] offset:128
	v_add_u32_e32 v6, 0x23000, v4
	global_atomic_add_f32 v6, v66, s[0:1] offset:-4096
	global_atomic_add_f32 v6, v50, s[0:1] offset:-3968
	global_atomic_add_f32 v6, v67, s[0:1] offset:0
	global_atomic_add_f32 v6, v51, s[0:1] offset:128
	v_add_u32_e32 v7, 0x29000, v4
	global_atomic_add_f32 v7, v68, s[0:1] offset:-4096
	global_atomic_add_f32 v7, v52, s[0:1] offset:-3968
	global_atomic_add_f32 v7, v69, s[0:1] offset:0
	global_atomic_add_f32 v7, v53, s[0:1] offset:128
	v_add_u32_e32 v8, 0x2b000, v4
	global_atomic_add_f32 v8, v70, s[0:1] offset:-4096
	global_atomic_add_f32 v8, v54, s[0:1] offset:-3968
	global_atomic_add_f32 v8, v71, s[0:1] offset:0
	global_atomic_add_f32 v8, v55, s[0:1] offset:128
	v_add_u32_e32 v9, 0x31000, v4
	global_atomic_add_f32 v9, v72, s[0:1] offset:-4096
	global_atomic_add_f32 v9, v56, s[0:1] offset:-3968
	global_atomic_add_f32 v9, v73, s[0:1] offset:0
	global_atomic_add_f32 v9, v57, s[0:1] offset:128
	v_add_u32_e32 v10, 0x33000, v4
	global_atomic_add_f32 v10, v74, s[0:1] offset:-4096
	global_atomic_add_f32 v10, v58, s[0:1] offset:-3968
	global_atomic_add_f32 v10, v75, s[0:1] offset:0
	global_atomic_add_f32 v10, v59, s[0:1] offset:128
	v_add_u32_e32 v11, 0x39000, v4
	global_atomic_add_f32 v11, v76, s[0:1] offset:-4096
	global_atomic_add_f32 v11, v60, s[0:1] offset:-3968
	global_atomic_add_f32 v11, v77, s[0:1] offset:0
	global_atomic_add_f32 v11, v61, s[0:1] offset:128
	v_add_u32_e32 v12, 0x3b000, v4
	global_atomic_add_f32 v12, v78, s[0:1] offset:-4096
	global_atomic_add_f32 v12, v62, s[0:1] offset:-3968
	global_atomic_add_f32 v12, v79, s[0:1] offset:0
	global_atomic_add_f32 v12, v63, s[0:1] offset:128
	v_lshl_add_u32 v3, s59, 12, v4
	v_add_u32_e32 v5, 0x1000, v3
	global_atomic_add_f32 v5, v32, s[0:1] offset:-4096
	global_atomic_add_f32 v5, v16, s[0:1] offset:-3968
	global_atomic_add_f32 v5, v33, s[0:1] offset:0
	global_atomic_add_f32 v5, v17, s[0:1] offset:128
	v_add_u32_e32 v6, 0x3000, v3
	global_atomic_add_f32 v6, v34, s[0:1] offset:-4096
	global_atomic_add_f32 v6, v18, s[0:1] offset:-3968
	global_atomic_add_f32 v6, v35, s[0:1] offset:0
	global_atomic_add_f32 v6, v19, s[0:1] offset:128
	v_add_u32_e32 v7, 0x9000, v3
	global_atomic_add_f32 v7, v36, s[0:1] offset:-4096
	global_atomic_add_f32 v7, v20, s[0:1] offset:-3968
	global_atomic_add_f32 v7, v37, s[0:1] offset:0
	global_atomic_add_f32 v7, v21, s[0:1] offset:128
	v_add_u32_e32 v8, 0xb000, v3
	global_atomic_add_f32 v8, v38, s[0:1] offset:-4096
	global_atomic_add_f32 v8, v22, s[0:1] offset:-3968
	global_atomic_add_f32 v8, v39, s[0:1] offset:0
	global_atomic_add_f32 v8, v23, s[0:1] offset:128
	v_add_u32_e32 v9, 0x11000, v3
	global_atomic_add_f32 v9, v40, s[0:1] offset:-4096
	global_atomic_add_f32 v9, v24, s[0:1] offset:-3968
	global_atomic_add_f32 v9, v41, s[0:1] offset:0
	global_atomic_add_f32 v9, v25, s[0:1] offset:128
	v_add_u32_e32 v10, 0x13000, v3
	global_atomic_add_f32 v10, v42, s[0:1] offset:-4096
	global_atomic_add_f32 v10, v26, s[0:1] offset:-3968
	global_atomic_add_f32 v10, v43, s[0:1] offset:0
	global_atomic_add_f32 v10, v27, s[0:1] offset:128
	v_add_u32_e32 v11, 0x19000, v3
	global_atomic_add_f32 v11, v44, s[0:1] offset:-4096
	global_atomic_add_f32 v11, v28, s[0:1] offset:-3968
	global_atomic_add_f32 v11, v45, s[0:1] offset:0
	global_atomic_add_f32 v11, v29, s[0:1] offset:128
	v_add_u32_e32 v12, 0x1b000, v3
	global_atomic_add_f32 v12, v46, s[0:1] offset:-4096
	global_atomic_add_f32 v12, v30, s[0:1] offset:-3968
	global_atomic_add_f32 v12, v47, s[0:1] offset:0
	global_atomic_add_f32 v12, v31, s[0:1] offset:128
	s_waitcnt vmcnt(0)
	s_branch .LBB0_444

; DI int otid() { int t = threadIdx.x; asm volatile("" : "+v"(t)); return t; }
; DI int crow(int i, int h) { return (i & 3) + 8 * (i >> 2) + 4 * h; }
; DI const bf16_t* wp(const Params& p, int l, size_t off) { return (const bf16_t*)(p.ws + OFF_WP) + (size_t)l * PW_LAYER + off; }
;     DI void operator()(int unit, const f32x16 (&acc)[MT][NT]) const {
;         const int lane = otid() & 63, r = lane & 31, h = lane >> 5;
; #pragma unroll
;         for (int mi = 0; mi < MT; ++mi)
; #pragma unroll
;             for (int nj = 0; nj < NT; ++nj)
; #pragma unroll
;                 for (int i = 0; i < 16; ++i) { float* q = x + ((mi * 32 + crow(i, h) + (mi == 2 ? d2 : 0)) * DM + unit * UW + nj * 32 + r); *q = *q + acc[mi][nj][i]; if (i == 15) __builtin_amdgcn_sched_barrier(0); }
; template <int MT> DI void phaseC(const Params& p, int l, int t, unsigned char* lds) {
;     ...
;     gemm64<DFF, MT>(priv, PRIVW, d2, wp(p, l, PW_DOWN), DM / UW, lds, EpiResid<MT>{x, d2});
.LBB0_814:
	s_and_saveexec_b64 s[56:57], s[6:7]
	s_cbranch_execz .LBB0_803
	s_waitcnt vmcnt(0)
	v_and_b32_e32 v2, 31, v176
	v_lshlrev_b32_e32 v112, 9, v176
	v_and_b32_e32 v112, 0x4000, v112
	v_lshl_or_b32 v113, v2, 2, v112
	v_lshl_add_u32 v113, v232, 8, v113
	v_add_u32_e32 v114, 0x1000, v113
	global_atomic_add_f32 v114, v96, s[8:9] offset:-4096
	global_atomic_add_f32 v114, v80, s[8:9] offset:-3968
	global_atomic_add_f32 v114, v97, s[8:9] offset:0
	global_atomic_add_f32 v114, v81, s[8:9] offset:128
	v_add_u32_e32 v116, 0x3000, v113
	global_atomic_add_f32 v116, v98, s[8:9] offset:-4096
	global_atomic_add_f32 v116, v82, s[8:9] offset:-3968
	global_atomic_add_f32 v116, v99, s[8:9] offset:0
	global_atomic_add_f32 v116, v83, s[8:9] offset:128
	v_add_u32_e32 v117, 0x9000, v113
	global_atomic_add_f32 v117, v100, s[8:9] offset:-4096
	global_atomic_add_f32 v117, v84, s[8:9] offset:-3968
	global_atomic_add_f32 v117, v101, s[8:9] offset:0
	global_atomic_add_f32 v117, v85, s[8:9] offset:128
	v_add_u32_e32 v118, 0xb000, v113
	global_atomic_add_f32 v118, v102, s[8:9] offset:-4096
	global_atomic_add_f32 v118, v86, s[8:9] offset:-3968
	global_atomic_add_f32 v118, v103, s[8:9] offset:0
	global_atomic_add_f32 v118, v87, s[8:9] offset:128
	v_add_u32_e32 v119, 0x11000, v113
	global_atomic_add_f32 v119, v104, s[8:9] offset:-4096
	global_atomic_add_f32 v119, v88, s[8:9] offset:-3968
	global_atomic_add_f32 v119, v105, s[8:9] offset:0
	global_atomic_add_f32 v119, v89, s[8:9] offset:128
	v_add_u32_e32 v120, 0x13000, v113
	global_atomic_add_f32 v120, v106, s[8:9] offset:-4096
	global_atomic_add_f32 v120, v90, s[8:9] offset:-3968
	global_atomic_add_f32 v120, v107, s[8:9] offset:0
	global_atomic_add_f32 v120, v91, s[8:9] offset:128
	v_add_u32_e32 v121, 0x19000, v113
	global_atomic_add_f32 v121, v108, s[8:9] offset:-4096
	global_atomic_add_f32 v121, v92, s[8:9] offset:-3968
	global_atomic_add_f32 v121, v109, s[8:9] offset:0
	global_atomic_add_f32 v121, v93, s[8:9] offset:128
	v_add_u32_e32 v122, 0x1b000, v113
	global_atomic_add_f32 v122, v110, s[8:9] offset:-4096
	global_atomic_add_f32 v122, v94, s[8:9] offset:-3968
	global_atomic_add_f32 v122, v111, s[8:9] offset:0
	global_atomic_add_f32 v122, v95, s[8:9] offset:128
	v_add_u32_e32 v114, 0x21000, v113
	global_atomic_add_f32 v114, v64, s[8:9] offset:-4096
	global_atomic_add_f32 v114, v48, s[8:9] offset:-3968
	global_atomic_add_f32 v114, v65, s[8:9] offset:0
	global_atomic_add_f32 v114, v49, s[8:9] offset:128
	v_add_u32_e32 v116, 0x23000, v113
	global_atomic_add_f32 v116, v66, s[8:9] offset:-4096
	global_atomic_add_f32 v116, v50, s[8:9] offset:-3968
	global_atomic_add_f32 v116, v67, s[8:9] offset:0
	global_atomic_add_f32 v116, v51, s[8:9] offset:128
	v_add_u32_e32 v117, 0x29000, v113
	global_atomic_add_f32 v117, v68, s[8:9] offset:-4096
	global_atomic_add_f32 v117, v52, s[8:9] offset:-3968
	global_atomic_add_f32 v117, v69, s[8:9] offset:0
	global_atomic_add_f32 v117, v53, s[8:9] offset:128
	v_add_u32_e32 v118, 0x2b000, v113
	global_atomic_add_f32 v118, v70, s[8:9] offset:-4096
	global_atomic_add_f32 v118, v54, s[8:9] offset:-3968
	global_atomic_add_f32 v118, v71, s[8:9] offset:0
	global_atomic_add_f32 v118, v55, s[8:9] offset:128
	v_add_u32_e32 v119, 0x31000, v113
	global_atomic_add_f32 v119, v72, s[8:9] offset:-4096
	global_atomic_add_f32 v119, v56, s[8:9] offset:-3968
	global_atomic_add_f32 v119, v73, s[8:9] offset:0
	global_atomic_add_f32 v119, v57, s[8:9] offset:128
	v_add_u32_e32 v120, 0x33000, v113
	global_atomic_add_f32 v120, v74, s[8:9] offset:-4096
	global_atomic_add_f32 v120, v58, s[8:9] offset:-3968
	global_atomic_add_f32 v120, v75, s[8:9] offset:0
	global_atomic_add_f32 v120, v59, s[8:9] offset:128
	v_add_u32_e32 v121, 0x39000, v113
	global_atomic_add_f32 v121, v76, s[8:9] offset:-4096
	global_atomic_add_f32 v121, v60, s[8:9] offset:-3968
	global_atomic_add_f32 v121, v77, s[8:9] offset:0
	global_atomic_add_f32 v121, v61, s[8:9] offset:128
	v_add_u32_e32 v122, 0x3b000, v113
	global_atomic_add_f32 v122, v78, s[8:9] offset:-4096
	global_atomic_add_f32 v122, v62, s[8:9] offset:-3968
	global_atomic_add_f32 v122, v79, s[8:9] offset:0
	global_atomic_add_f32 v122, v63, s[8:9] offset:128
	s_sub_i32 s100, 0x4000, s94
	v_lshl_add_u32 v112, s100, 12, v113
	v_add_u32_e32 v114, 0x1000, v112
	global_atomic_add_f32 v114, v32, s[8:9] offset:-4096
	global_atomic_add_f32 v114, v16, s[8:9] offset:-3968
	global_atomic_add_f32 v114, v33, s[8:9] offset:0
	global_atomic_add_f32 v114, v17, s[8:9] offset:128
	v_add_u32_e32 v116, 0x3000, v112
	global_atomic_add_f32 v116, v34, s[8:9] offset:-4096
	global_atomic_add_f32 v116, v18, s[8:9] offset:-3968
	global_atomic_add_f32 v116, v35, s[8:9] offset:0
	global_atomic_add_f32 v116, v19, s[8:9] offset:128
	v_add_u32_e32 v117, 0x9000, v112
	global_atomic_add_f32 v117, v36, s[8:9] offset:-4096
	global_atomic_add_f32 v117, v20, s[8:9] offset:-3968
	global_atomic_add_f32 v117, v37, s[8:9] offset:0
	global_atomic_add_f32 v117, v21, s[8:9] offset:128
	v_add_u32_e32 v118, 0xb000, v112
	global_atomic_add_f32 v118, v38, s[8:9] offset:-4096
	global_atomic_add_f32 v118, v22, s[8:9] offset:-3968
	global_atomic_add_f32 v118, v39, s[8:9] offset:0
	global_atomic_add_f32 v118, v23, s[8:9] offset:128
	v_add_u32_e32 v119, 0x11000, v112
	global_atomic_add_f32 v119, v40, s[8:9] offset:-4096
	global_atomic_add_f32 v119, v24, s[8:9] offset:-3968
	global_atomic_add_f32 v119, v41, s[8:9] offset:0
	global_atomic_add_f32 v119, v25, s[8:9] offset:128
	v_add_u32_e32 v120, 0x13000, v112
	global_atomic_add_f32 v120, v42, s[8:9] offset:-4096
	global_atomic_add_f32 v120, v26, s[8:9] offset:-3968
	global_atomic_add_f32 v120, v43, s[8:9] offset:0
	global_atomic_add_f32 v120, v27, s[8:9] offset:128
	v_add_u32_e32 v121, 0x19000, v112
	global_atomic_add_f32 v121, v44, s[8:9] offset:-4096
	global_atomic_add_f32 v121, v28, s[8:9] offset:-3968
	global_atomic_add_f32 v121, v45, s[8:9] offset:0
	global_atomic_add_f32 v121, v29, s[8:9] offset:128
	v_add_u32_e32 v122, 0x1b000, v112
	global_atomic_add_f32 v122, v46, s[8:9] offset:-4096
	global_atomic_add_f32 v122, v30, s[8:9] offset:-3968
	global_atomic_add_f32 v122, v47, s[8:9] offset:0
	global_atomic_add_f32 v122, v31, s[8:9] offset:128
	s_waitcnt vmcnt(0)
	s_branch .LBB0_803
